# barrier: early L1 invalidate at arrival + per-XCD completion count checked by the XCD leader (no invalidate after release)
# speedup vs baseline: 1.0111x; 1.0039x over previous
.LBB0_163:
	s_or_b64 exec, exec, s[2:3]
	s_cmp_eq_u32 s71, 2
	s_cbranch_scc1 .LBB0_226
	s_cmp_lg_u32 s70, 1
	s_mov_b64 s[2:3], -1
	s_cbranch_scc0 .LBB0_214
	s_waitcnt vmcnt(0)
	s_barrier
	s_mov_b64 s[2:3], exec
	v_readlane_b32 s4, v253, 6
	v_readlane_b32 s5, v253, 7
	s_and_b64 s[4:5], s[2:3], s[4:5]
	s_mov_b64 exec, s[4:5]
	s_cbranch_execz .LBB0_213
	v_readlane_b32 s98, v253, 2
	v_readlane_b32 s99, v253, 3
	v_mov_b32_e32 v1, 0x12000
	s_waitcnt vmcnt(0) expcnt(0) lgkmcnt(0)
	s_load_dwordx2 s[98:99], s[98:99], 0xf8
	ds_read_b128 v[4:7], v1
	s_getreg_b32 s100, hwreg(HW_REG_XCC_ID, 0, 4)
	s_and_b32 s100, s100, 15
	s_lshl_b32 s100, s100, 8
	s_add_u32 s100, s100, 0x38e00000
	s_waitcnt lgkmcnt(0)
	s_add_u32 s100, s98, s100
	s_addc_u32 s101, s99, 0
	v_mov_b32_e32 v2, 1
	v_mov_b32_e32 v3, 0x1400
	global_atomic_add v8, v3, v2, s[100:101] sc0
	v_cvt_f32_u32_e32 v12, v4
	v_rcp_iflag_f32_e32 v12, v12
	v_sub_u32_e32 v13, 0, v4
	s_nop 1
	v_mul_f32_e32 v12, 0x4f7ffffe, v12
	v_cvt_u32_f32_e32 v12, v12
	v_mul_lo_u32 v13, v13, v12
	v_mul_hi_u32 v13, v12, v13
	v_add_u32_e32 v12, v12, v13
	s_waitcnt vmcnt(0)
	buffer_inv sc1
	v_mul_hi_u32 v12, v8, v12
	v_mul_lo_u32 v13, v12, v4
	v_sub_u32_e32 v14, v8, v13
	v_add_u32_e32 v15, 1, v12
	v_cmp_ge_u32_e32 vcc, v14, v4
	v_sub_u32_e32 v13, v14, v4
	s_nop 1
	v_cndmask_b32_e32 v12, v12, v15, vcc
	v_cndmask_b32_e32 v14, v14, v13, vcc
	v_add_u32_e32 v15, 1, v12
	v_cmp_ge_u32_e32 vcc, v14, v4
	s_nop 1
	v_cndmask_b32_e32 v6, v12, v15, vcc
	v_add_u32_e32 v9, 1, v6
	v_mul_lo_u32 v10, v9, v4
	v_mul_lo_u32 v11, v9, v5
	v_add_u32_e32 v8, 1, v8
	v_cmp_ne_u32_e32 vcc, v8, v10
	s_cbranch_vccnz .Lxb_spin_1
	v_mov_b32_e32 v3, 0x1480
	v_add_u32_e32 v14, -1, v4
	v_mul_lo_u32 v14, v14, v6
	buffer_wbl2 sc1
	v_mov_b32_e32 v16, 0
.Lxb_ipoll_1:
	global_load_dword v13, v3, s[100:101] sc1
	s_waitcnt vmcnt(0) lgkmcnt(0)
	v_cmp_eq_u32_e32 vcc, v13, v14
	s_cbranch_vccnz .Lxb_iok_1
	s_sleep 1
	v_add_u32_e32 v16, 1, v16
	v_cmp_gt_u32_e32 vcc, 0x4000, v16
	s_cbranch_vccnz .Lxb_ipoll_1
.Lxb_iok_1:
	v_mov_b32_e32 v3, 0x38e03400
	global_atomic_add v8, v3, v2, s[98:99] sc0
	s_waitcnt vmcnt(0)
	v_add_u32_e32 v8, 1, v8
	v_cmp_ne_u32_e32 vcc, v8, v11
	s_cbranch_vccnz .Lxb_spinl_1
	v_mov_b32_e32 v3, 0x38e03500
	global_atomic_add v3, v2, s[98:99]
	v_mov_b32_e32 v12, 0x38e02400
	global_atomic_add v12, v2, s[98:99]
	v_mov_b32_e32 v13, 0x38e02500
	global_atomic_add v13, v2, s[98:99]
	v_mov_b32_e32 v14, 0x38e02600
	global_atomic_add v14, v2, s[98:99]
	v_mov_b32_e32 v15, 0x38e02700
	global_atomic_add v15, v2, s[98:99]
	v_mov_b32_e32 v12, 0x38e02800
	global_atomic_add v12, v2, s[98:99]
	v_mov_b32_e32 v13, 0x38e02900
	global_atomic_add v13, v2, s[98:99]
	v_mov_b32_e32 v14, 0x38e02a00
	global_atomic_add v14, v2, s[98:99]
	v_mov_b32_e32 v15, 0x38e02b00
	global_atomic_add v15, v2, s[98:99]
	v_mov_b32_e32 v12, 0x38e02c00
	global_atomic_add v12, v2, s[98:99]
	v_mov_b32_e32 v13, 0x38e02d00
	global_atomic_add v13, v2, s[98:99]
	v_mov_b32_e32 v14, 0x38e02e00
	global_atomic_add v14, v2, s[98:99]
	v_mov_b32_e32 v15, 0x38e02f00
	global_atomic_add v15, v2, s[98:99]
	v_mov_b32_e32 v12, 0x38e03000
	global_atomic_add v12, v2, s[98:99]
	v_mov_b32_e32 v13, 0x38e03100
	global_atomic_add v13, v2, s[98:99]
	v_mov_b32_e32 v14, 0x38e03200
	global_atomic_add v14, v2, s[98:99]
	v_mov_b32_e32 v15, 0x38e03300
	global_atomic_add v15, v2, s[98:99]
	s_branch .Lxb_done_1
.Lxb_spin_1:
	s_waitcnt vmcnt(0)
	v_mov_b32_e32 v3, 0x1480
	global_atomic_add v3, v2, s[100:101]

.LBB0_271:
	s_add_i32 s2, s30, 1
	s_cmp_ge_i32 s2, s71
	s_cbranch_scc1 .LBB0_284
	s_cmp_lg_u32 s30, s70
	s_mov_b64 s[44:45], -1
	s_cbranch_scc0 .LBB0_323
	s_waitcnt vmcnt(0)
	s_barrier
	s_mov_b64 s[44:45], exec
	v_readlane_b32 s38, v253, 6
	v_readlane_b32 s39, v253, 7
	s_and_b64 s[38:39], s[44:45], s[38:39]
	s_mov_b64 exec, s[38:39]
	s_cbranch_execz .LBB0_322
	v_readlane_b32 s98, v253, 2
	v_readlane_b32 s99, v253, 3
	v_mov_b32_e32 v1, 0x12000
	s_waitcnt vmcnt(0) expcnt(0) lgkmcnt(0)
	s_load_dwordx2 s[98:99], s[98:99], 0xf8
	ds_read_b128 v[4:7], v1
	s_getreg_b32 s100, hwreg(HW_REG_XCC_ID, 0, 4)
	s_and_b32 s100, s100, 15
	s_lshl_b32 s100, s100, 8
	s_add_u32 s100, s100, 0x38e00000
	s_waitcnt lgkmcnt(0)
	s_add_u32 s100, s98, s100
	s_addc_u32 s101, s99, 0
	v_mov_b32_e32 v2, 1
	v_mov_b32_e32 v3, 0x1400
	global_atomic_add v8, v3, v2, s[100:101] sc0
	v_cvt_f32_u32_e32 v12, v4
	v_rcp_iflag_f32_e32 v12, v12
	v_sub_u32_e32 v13, 0, v4
	s_nop 1
	v_mul_f32_e32 v12, 0x4f7ffffe, v12
	v_cvt_u32_f32_e32 v12, v12
	v_mul_lo_u32 v13, v13, v12
	v_mul_hi_u32 v13, v12, v13
	v_add_u32_e32 v12, v12, v13
	s_waitcnt vmcnt(0)
	buffer_inv sc1
	v_mul_hi_u32 v12, v8, v12
	v_mul_lo_u32 v13, v12, v4
	v_sub_u32_e32 v14, v8, v13
	v_add_u32_e32 v15, 1, v12
	v_cmp_ge_u32_e32 vcc, v14, v4
	v_sub_u32_e32 v13, v14, v4
	s_nop 1
	v_cndmask_b32_e32 v12, v12, v15, vcc
	v_cndmask_b32_e32 v14, v14, v13, vcc
	v_add_u32_e32 v15, 1, v12
	v_cmp_ge_u32_e32 vcc, v14, v4
	s_nop 1
	v_cndmask_b32_e32 v6, v12, v15, vcc
	v_add_u32_e32 v9, 1, v6
	v_mul_lo_u32 v10, v9, v4
	v_mul_lo_u32 v11, v9, v5
	v_add_u32_e32 v8, 1, v8
	v_cmp_ne_u32_e32 vcc, v8, v10
	s_cbranch_vccnz .Lxb_spin_2
	v_mov_b32_e32 v3, 0x1480
	v_add_u32_e32 v14, -1, v4
	v_mul_lo_u32 v14, v14, v6
	buffer_wbl2 sc1
	v_mov_b32_e32 v16, 0

.LBB0_384:
	s_add_i32 s31, s30, 2
	s_cmp_ge_i32 s31, s71
	s_cbranch_scc1 .LBB0_447
	s_cmp_lg_u32 s2, s70
	s_mov_b64 s[44:45], -1
	s_cbranch_scc0 .LBB0_435
	s_waitcnt vmcnt(0)
	s_barrier
	s_mov_b64 s[44:45], exec
	v_readlane_b32 s2, v253, 6
	v_readlane_b32 s3, v253, 7
	s_and_b64 s[2:3], s[44:45], s[2:3]
	s_mov_b64 exec, s[2:3]
	s_cbranch_execz .LBB0_434
	v_readlane_b32 s98, v253, 2
	v_readlane_b32 s99, v253, 3
	v_mov_b32_e32 v1, 0x12000
	s_waitcnt vmcnt(0) expcnt(0) lgkmcnt(0)
	s_load_dwordx2 s[98:99], s[98:99], 0xf8
	ds_read_b128 v[4:7], v1
	s_getreg_b32 s100, hwreg(HW_REG_XCC_ID, 0, 4)
	s_and_b32 s100, s100, 15
	s_lshl_b32 s100, s100, 8
	s_add_u32 s100, s100, 0x38e00000
	s_waitcnt lgkmcnt(0)
	s_add_u32 s100, s98, s100
	s_addc_u32 s101, s99, 0
	v_mov_b32_e32 v2, 1
	v_mov_b32_e32 v3, 0x1400
	global_atomic_add v8, v3, v2, s[100:101] sc0
	v_cvt_f32_u32_e32 v12, v4
	v_rcp_iflag_f32_e32 v12, v12
	v_sub_u32_e32 v13, 0, v4
	s_nop 1
	v_mul_f32_e32 v12, 0x4f7ffffe, v12
	v_cvt_u32_f32_e32 v12, v12
	v_mul_lo_u32 v13, v13, v12
	v_mul_hi_u32 v13, v12, v13
	v_add_u32_e32 v12, v12, v13
	s_waitcnt vmcnt(0)
	buffer_inv sc1
	v_mul_hi_u32 v12, v8, v12
	v_mul_lo_u32 v13, v12, v4
	v_sub_u32_e32 v14, v8, v13
	v_add_u32_e32 v15, 1, v12
	v_cmp_ge_u32_e32 vcc, v14, v4
	v_sub_u32_e32 v13, v14, v4
	s_nop 1
	v_cndmask_b32_e32 v12, v12, v15, vcc
	v_cndmask_b32_e32 v14, v14, v13, vcc
	v_add_u32_e32 v15, 1, v12
	v_cmp_ge_u32_e32 vcc, v14, v4
	s_nop 1
	v_cndmask_b32_e32 v6, v12, v15, vcc
	v_add_u32_e32 v9, 1, v6
	v_mul_lo_u32 v10, v9, v4
	v_mul_lo_u32 v11, v9, v5
	v_add_u32_e32 v8, 1, v8
	v_cmp_ne_u32_e32 vcc, v8, v10
	s_cbranch_vccnz .Lxb_spin_3
	v_mov_b32_e32 v3, 0x1480
	v_add_u32_e32 v14, -1, v4
	v_mul_lo_u32 v14, v14, v6
	buffer_wbl2 sc1
	v_mov_b32_e32 v16, 0

.LBB0_459:
	s_add_i32 s31, s30, 1
	s_cmp_ge_i32 s31, s71
	s_cbranch_scc1 .LBB0_522
	s_cmp_lg_u32 s30, s70
	s_mov_b64 s[42:43], -1
	s_cbranch_scc0 .LBB0_510
	s_waitcnt vmcnt(0)
	s_barrier
	s_mov_b64 s[42:43], exec
	v_readlane_b32 s2, v253, 6
	v_readlane_b32 s3, v253, 7
	s_and_b64 s[2:3], s[42:43], s[2:3]
	s_mov_b64 exec, s[2:3]
	s_cbranch_execz .LBB0_509
	v_readlane_b32 s98, v253, 2
	v_readlane_b32 s99, v253, 3
	v_mov_b32_e32 v1, 0x12000
	s_waitcnt vmcnt(0) expcnt(0) lgkmcnt(0)
	s_load_dwordx2 s[98:99], s[98:99], 0xf8
	ds_read_b128 v[4:7], v1
	s_getreg_b32 s100, hwreg(HW_REG_XCC_ID, 0, 4)
	s_and_b32 s100, s100, 15
	s_lshl_b32 s100, s100, 8
	s_add_u32 s100, s100, 0x38e00000
	s_waitcnt lgkmcnt(0)
	s_add_u32 s100, s98, s100
	s_addc_u32 s101, s99, 0
	v_mov_b32_e32 v2, 1
	v_mov_b32_e32 v3, 0x1400
	global_atomic_add v8, v3, v2, s[100:101] sc0
	v_cvt_f32_u32_e32 v12, v4
	v_rcp_iflag_f32_e32 v12, v12
	v_sub_u32_e32 v13, 0, v4
	s_nop 1
	v_mul_f32_e32 v12, 0x4f7ffffe, v12
	v_cvt_u32_f32_e32 v12, v12
	v_mul_lo_u32 v13, v13, v12
	v_mul_hi_u32 v13, v12, v13
	v_add_u32_e32 v12, v12, v13
	s_waitcnt vmcnt(0)
	buffer_inv sc1
	v_mul_hi_u32 v12, v8, v12
	v_mul_lo_u32 v13, v12, v4
	v_sub_u32_e32 v14, v8, v13
	v_add_u32_e32 v15, 1, v12
	v_cmp_ge_u32_e32 vcc, v14, v4
	v_sub_u32_e32 v13, v14, v4
	s_nop 1
	v_cndmask_b32_e32 v12, v12, v15, vcc
	v_cndmask_b32_e32 v14, v14, v13, vcc
	v_add_u32_e32 v15, 1, v12
	v_cmp_ge_u32_e32 vcc, v14, v4
	s_nop 1
	v_cndmask_b32_e32 v6, v12, v15, vcc
	v_add_u32_e32 v9, 1, v6
	v_mul_lo_u32 v10, v9, v4
	v_mul_lo_u32 v11, v9, v5
	v_add_u32_e32 v8, 1, v8
	v_cmp_ne_u32_e32 vcc, v8, v10
	s_cbranch_vccnz .Lxb_spin_4
	v_mov_b32_e32 v3, 0x1480
	v_add_u32_e32 v14, -1, v4
	v_mul_lo_u32 v14, v14, v6
	buffer_wbl2 sc1
	v_mov_b32_e32 v16, 0

.LBB0_641:
	s_add_i32 s3, s30, 2
	s_cmp_ge_i32 s3, s71
	s_cbranch_scc1 .LBB0_704
	s_cmp_lg_u32 s31, s70
	s_mov_b64 s[42:43], -1
	s_cbranch_scc0 .LBB0_692
	s_waitcnt vmcnt(0)
	s_waitcnt lgkmcnt(0)
	s_barrier
	s_mov_b64 s[42:43], exec
	v_readlane_b32 s38, v253, 6
	v_readlane_b32 s39, v253, 7
	s_and_b64 s[38:39], s[42:43], s[38:39]
	s_mov_b64 exec, s[38:39]
	s_cbranch_execz .LBB0_691
	v_readlane_b32 s98, v253, 2
	v_readlane_b32 s99, v253, 3
	v_mov_b32_e32 v1, 0x12000
	s_waitcnt vmcnt(0) expcnt(0) lgkmcnt(0)
	s_load_dwordx2 s[98:99], s[98:99], 0xf8
	ds_read_b128 v[4:7], v1
	s_getreg_b32 s100, hwreg(HW_REG_XCC_ID, 0, 4)
	s_and_b32 s100, s100, 15
	s_lshl_b32 s100, s100, 8
	s_add_u32 s100, s100, 0x38e00000
	s_waitcnt lgkmcnt(0)
	s_add_u32 s100, s98, s100
	s_addc_u32 s101, s99, 0
	v_mov_b32_e32 v2, 1
	v_mov_b32_e32 v3, 0x1400
	global_atomic_add v8, v3, v2, s[100:101] sc0
	v_cvt_f32_u32_e32 v12, v4
	v_rcp_iflag_f32_e32 v12, v12
	v_sub_u32_e32 v13, 0, v4
	s_nop 1
	v_mul_f32_e32 v12, 0x4f7ffffe, v12
	v_cvt_u32_f32_e32 v12, v12
	v_mul_lo_u32 v13, v13, v12
	v_mul_hi_u32 v13, v12, v13
	v_add_u32_e32 v12, v12, v13
	s_waitcnt vmcnt(0)
	buffer_inv sc1
	v_mul_hi_u32 v12, v8, v12
	v_mul_lo_u32 v13, v12, v4
	v_sub_u32_e32 v14, v8, v13
	v_add_u32_e32 v15, 1, v12
	v_cmp_ge_u32_e32 vcc, v14, v4
	v_sub_u32_e32 v13, v14, v4
	s_nop 1
	v_cndmask_b32_e32 v12, v12, v15, vcc
	v_cndmask_b32_e32 v14, v14, v13, vcc
	v_add_u32_e32 v15, 1, v12
	v_cmp_ge_u32_e32 vcc, v14, v4
	s_nop 1
	v_cndmask_b32_e32 v6, v12, v15, vcc
	v_add_u32_e32 v9, 1, v6
	v_mul_lo_u32 v10, v9, v4
	v_mul_lo_u32 v11, v9, v5
	v_add_u32_e32 v8, 1, v8
	v_cmp_ne_u32_e32 vcc, v8, v10
	s_cbranch_vccnz .Lxb_spin_5
	v_mov_b32_e32 v3, 0x1480
	v_add_u32_e32 v14, -1, v4
	v_mul_lo_u32 v14, v14, v6
	buffer_wbl2 sc1
	v_mov_b32_e32 v16, 0

.LBB0_714:
	s_or_b64 exec, exec, s[44:45]
	s_add_i32 s2, s30, 3
	s_cmp_ge_i32 s2, s71
	s_cbranch_scc1 .LBB0_777
	s_cmp_lg_u32 s3, s70
	s_mov_b64 s[42:43], -1
	s_cbranch_scc0 .LBB0_765
	s_waitcnt vmcnt(0)
	s_waitcnt lgkmcnt(0)
	s_barrier
	s_mov_b64 s[42:43], exec
	v_readlane_b32 s38, v253, 6
	v_readlane_b32 s39, v253, 7
	s_and_b64 s[38:39], s[42:43], s[38:39]
	s_mov_b64 exec, s[38:39]
	s_cbranch_execz .LBB0_764
	v_readlane_b32 s98, v253, 2
	v_readlane_b32 s99, v253, 3
	v_mov_b32_e32 v1, 0x12000
	s_waitcnt vmcnt(0) expcnt(0) lgkmcnt(0)
	s_load_dwordx2 s[98:99], s[98:99], 0xf8
	ds_read_b128 v[4:7], v1
	s_getreg_b32 s100, hwreg(HW_REG_XCC_ID, 0, 4)
	s_and_b32 s100, s100, 15
	s_lshl_b32 s100, s100, 8
	s_add_u32 s100, s100, 0x38e00000
	s_waitcnt lgkmcnt(0)
	s_add_u32 s100, s98, s100
	s_addc_u32 s101, s99, 0
	v_mov_b32_e32 v2, 1
	v_mov_b32_e32 v3, 0x1400
	global_atomic_add v8, v3, v2, s[100:101] sc0
	v_cvt_f32_u32_e32 v12, v4
	v_rcp_iflag_f32_e32 v12, v12
	v_sub_u32_e32 v13, 0, v4
	s_nop 1
	v_mul_f32_e32 v12, 0x4f7ffffe, v12
	v_cvt_u32_f32_e32 v12, v12
	v_mul_lo_u32 v13, v13, v12
	v_mul_hi_u32 v13, v12, v13
	v_add_u32_e32 v12, v12, v13
	s_waitcnt vmcnt(0)
	buffer_inv sc1
	v_mul_hi_u32 v12, v8, v12
	v_mul_lo_u32 v13, v12, v4
	v_sub_u32_e32 v14, v8, v13
	v_add_u32_e32 v15, 1, v12
	v_cmp_ge_u32_e32 vcc, v14, v4
	v_sub_u32_e32 v13, v14, v4
	s_nop 1
	v_cndmask_b32_e32 v12, v12, v15, vcc
	v_cndmask_b32_e32 v14, v14, v13, vcc
	v_add_u32_e32 v15, 1, v12
	v_cmp_ge_u32_e32 vcc, v14, v4
	s_nop 1
	v_cndmask_b32_e32 v6, v12, v15, vcc
	v_add_u32_e32 v9, 1, v6
	v_mul_lo_u32 v10, v9, v4
	v_mul_lo_u32 v11, v9, v5
	v_add_u32_e32 v8, 1, v8
	v_cmp_ne_u32_e32 vcc, v8, v10
	s_cbranch_vccnz .Lxb_spin_6
	v_mov_b32_e32 v3, 0x1480
	v_add_u32_e32 v14, -1, v4
	v_mul_lo_u32 v14, v14, v6
	buffer_wbl2 sc1
	v_mov_b32_e32 v16, 0

.LBB0_789:
	s_add_i32 s31, s30, 4
	s_cmp_ge_i32 s31, s71
	s_cbranch_scc1 .LBB0_852
	s_cmp_lg_u32 s2, s70
	s_mov_b64 s[42:43], -1
	s_cbranch_scc0 .LBB0_840
	s_waitcnt vmcnt(0)
	s_waitcnt lgkmcnt(0)
	s_barrier
	s_mov_b64 s[42:43], exec
	v_readlane_b32 s2, v253, 6
	v_readlane_b32 s3, v253, 7
	s_and_b64 s[2:3], s[42:43], s[2:3]
	s_mov_b64 exec, s[2:3]
	s_cbranch_execz .LBB0_839
	v_readlane_b32 s98, v253, 2
	v_readlane_b32 s99, v253, 3
	v_mov_b32_e32 v1, 0x12000
	s_waitcnt vmcnt(0) expcnt(0) lgkmcnt(0)
	s_load_dwordx2 s[98:99], s[98:99], 0xf8
	ds_read_b128 v[4:7], v1
	s_getreg_b32 s100, hwreg(HW_REG_XCC_ID, 0, 4)
	s_and_b32 s100, s100, 15
	s_lshl_b32 s100, s100, 8
	s_add_u32 s100, s100, 0x38e00000
	s_waitcnt lgkmcnt(0)
	s_add_u32 s100, s98, s100
	s_addc_u32 s101, s99, 0
	v_mov_b32_e32 v2, 1
	v_mov_b32_e32 v3, 0x1400
	global_atomic_add v8, v3, v2, s[100:101] sc0
	v_cvt_f32_u32_e32 v12, v4
	v_rcp_iflag_f32_e32 v12, v12
	v_sub_u32_e32 v13, 0, v4
	s_nop 1
	v_mul_f32_e32 v12, 0x4f7ffffe, v12
	v_cvt_u32_f32_e32 v12, v12
	v_mul_lo_u32 v13, v13, v12
	v_mul_hi_u32 v13, v12, v13
	v_add_u32_e32 v12, v12, v13
	s_waitcnt vmcnt(0)
	buffer_inv sc1
	v_mul_hi_u32 v12, v8, v12
	v_mul_lo_u32 v13, v12, v4
	v_sub_u32_e32 v14, v8, v13
	v_add_u32_e32 v15, 1, v12
	v_cmp_ge_u32_e32 vcc, v14, v4
	v_sub_u32_e32 v13, v14, v4
	s_nop 1
	v_cndmask_b32_e32 v12, v12, v15, vcc
	v_cndmask_b32_e32 v14, v14, v13, vcc
	v_add_u32_e32 v15, 1, v12
	v_cmp_ge_u32_e32 vcc, v14, v4
	s_nop 1
	v_cndmask_b32_e32 v6, v12, v15, vcc
	v_add_u32_e32 v9, 1, v6
	v_mul_lo_u32 v10, v9, v4
	v_mul_lo_u32 v11, v9, v5
	v_add_u32_e32 v8, 1, v8
	v_cmp_ne_u32_e32 vcc, v8, v10
	s_cbranch_vccnz .Lxb_spin_7
	v_mov_b32_e32 v3, 0x1480
	v_add_u32_e32 v14, -1, v4
	v_mul_lo_u32 v14, v14, v6
	buffer_wbl2 sc1
	v_mov_b32_e32 v16, 0

.LBB0_862:
	s_add_i32 s2, s31, 1
	s_cmp_ge_i32 s2, s71
	s_cbranch_scc1 .LBB0_925
	s_cmp_lg_u32 s31, s70
	s_mov_b64 s[44:45], -1
	s_cbranch_scc0 .LBB0_913
	s_waitcnt vmcnt(0)
	s_waitcnt lgkmcnt(0)
	s_barrier
	s_mov_b64 s[44:45], exec
	v_readlane_b32 s38, v253, 6
	v_readlane_b32 s39, v253, 7
	s_and_b64 s[38:39], s[44:45], s[38:39]
	s_mov_b64 exec, s[38:39]
	s_cbranch_execz .LBB0_912
	v_readlane_b32 s98, v253, 2
	v_readlane_b32 s99, v253, 3
	v_mov_b32_e32 v1, 0x12000
	s_waitcnt vmcnt(0) expcnt(0) lgkmcnt(0)
	s_load_dwordx2 s[98:99], s[98:99], 0xf8
	ds_read_b128 v[4:7], v1
	s_getreg_b32 s100, hwreg(HW_REG_XCC_ID, 0, 4)
	s_and_b32 s100, s100, 15
	s_lshl_b32 s100, s100, 8
	s_add_u32 s100, s100, 0x38e00000
	s_waitcnt lgkmcnt(0)
	s_add_u32 s100, s98, s100
	s_addc_u32 s101, s99, 0
	v_mov_b32_e32 v2, 1
	v_mov_b32_e32 v3, 0x1400
	global_atomic_add v8, v3, v2, s[100:101] sc0
	v_cvt_f32_u32_e32 v12, v4
	v_rcp_iflag_f32_e32 v12, v12
	v_sub_u32_e32 v13, 0, v4
	s_nop 1
	v_mul_f32_e32 v12, 0x4f7ffffe, v12
	v_cvt_u32_f32_e32 v12, v12
	v_mul_lo_u32 v13, v13, v12
	v_mul_hi_u32 v13, v12, v13
	v_add_u32_e32 v12, v12, v13
	s_waitcnt vmcnt(0)
	buffer_inv sc1
	v_mul_hi_u32 v12, v8, v12
	v_mul_lo_u32 v13, v12, v4
	v_sub_u32_e32 v14, v8, v13
	v_add_u32_e32 v15, 1, v12
	v_cmp_ge_u32_e32 vcc, v14, v4
	v_sub_u32_e32 v13, v14, v4
	s_nop 1
	v_cndmask_b32_e32 v12, v12, v15, vcc
	v_cndmask_b32_e32 v14, v14, v13, vcc
	v_add_u32_e32 v15, 1, v12
	v_cmp_ge_u32_e32 vcc, v14, v4
	s_nop 1
	v_cndmask_b32_e32 v6, v12, v15, vcc
	v_add_u32_e32 v9, 1, v6
	v_mul_lo_u32 v10, v9, v4
	v_mul_lo_u32 v11, v9, v5
	v_add_u32_e32 v8, 1, v8
	v_cmp_ne_u32_e32 vcc, v8, v10
	s_cbranch_vccnz .Lxb_spin_8
	v_mov_b32_e32 v3, 0x1480
	v_add_u32_e32 v14, -1, v4
	v_mul_lo_u32 v14, v14, v6
	buffer_wbl2 sc1
	v_mov_b32_e32 v16, 0

.LBB0_933:
	s_or_b64 exec, exec, s[46:47]
	s_add_i32 s30, s31, 2
	s_cmp_ge_i32 s30, s71
	s_cbranch_scc1 .LBB0_996
	s_cmp_lg_u32 s2, s70
	s_mov_b64 s[44:45], -1
	s_cbranch_scc0 .LBB0_984
	s_waitcnt vmcnt(0)
	s_waitcnt lgkmcnt(0)
	s_barrier
	s_mov_b64 s[44:45], exec
	v_readlane_b32 s2, v253, 6
	v_readlane_b32 s3, v253, 7
	s_and_b64 s[2:3], s[44:45], s[2:3]
	s_mov_b64 exec, s[2:3]
	s_cbranch_execz .LBB0_983
	v_readlane_b32 s98, v253, 2
	v_readlane_b32 s99, v253, 3
	v_mov_b32_e32 v1, 0x12000
	s_waitcnt vmcnt(0) expcnt(0) lgkmcnt(0)
	s_load_dwordx2 s[98:99], s[98:99], 0xf8
	ds_read_b128 v[4:7], v1
	s_getreg_b32 s100, hwreg(HW_REG_XCC_ID, 0, 4)
	s_and_b32 s100, s100, 15
	s_lshl_b32 s100, s100, 8
	s_add_u32 s100, s100, 0x38e00000
	s_waitcnt lgkmcnt(0)
	s_add_u32 s100, s98, s100
	s_addc_u32 s101, s99, 0
	v_mov_b32_e32 v2, 1
	v_mov_b32_e32 v3, 0x1400
	global_atomic_add v8, v3, v2, s[100:101] sc0
	v_cvt_f32_u32_e32 v12, v4
	v_rcp_iflag_f32_e32 v12, v12
	v_sub_u32_e32 v13, 0, v4
	s_nop 1
	v_mul_f32_e32 v12, 0x4f7ffffe, v12
	v_cvt_u32_f32_e32 v12, v12
	v_mul_lo_u32 v13, v13, v12
	v_mul_hi_u32 v13, v12, v13
	v_add_u32_e32 v12, v12, v13
	s_waitcnt vmcnt(0)
	buffer_inv sc1
	v_mul_hi_u32 v12, v8, v12
	v_mul_lo_u32 v13, v12, v4
	v_sub_u32_e32 v14, v8, v13
	v_add_u32_e32 v15, 1, v12
	v_cmp_ge_u32_e32 vcc, v14, v4
	v_sub_u32_e32 v13, v14, v4
	s_nop 1
	v_cndmask_b32_e32 v12, v12, v15, vcc
	v_cndmask_b32_e32 v14, v14, v13, vcc
	v_add_u32_e32 v15, 1, v12
	v_cmp_ge_u32_e32 vcc, v14, v4
	s_nop 1
	v_cndmask_b32_e32 v6, v12, v15, vcc
	v_add_u32_e32 v9, 1, v6
	v_mul_lo_u32 v10, v9, v4
	v_mul_lo_u32 v11, v9, v5
	v_add_u32_e32 v8, 1, v8
	v_cmp_ne_u32_e32 vcc, v8, v10
	s_cbranch_vccnz .Lxb_spin_9
	v_mov_b32_e32 v3, 0x1480
	v_add_u32_e32 v14, -1, v4
	v_mul_lo_u32 v14, v14, v6
	buffer_wbl2 sc1
	v_mov_b32_e32 v16, 0

.LBB0_1007:
	s_add_i32 s92, s31, 3
	s_cmp_ge_i32 s92, s71
	s_cbranch_scc1 .LBB0_1070
	s_cmp_lg_u32 s30, s70
	s_mov_b64 s[42:43], -1
	s_cbranch_scc0 .LBB0_1058
	s_waitcnt vmcnt(0)
	s_waitcnt lgkmcnt(0)
	s_barrier
	s_mov_b64 s[42:43], exec
	v_readlane_b32 s2, v253, 6
	v_readlane_b32 s3, v253, 7
	s_and_b64 s[2:3], s[42:43], s[2:3]
	s_mov_b64 exec, s[2:3]
	s_cbranch_execz .LBB0_1057
	v_readlane_b32 s98, v253, 2
	v_readlane_b32 s99, v253, 3
	v_mov_b32_e32 v1, 0x12000
	s_waitcnt vmcnt(0) expcnt(0) lgkmcnt(0)
	s_load_dwordx2 s[98:99], s[98:99], 0xf8
	ds_read_b128 v[4:7], v1
	s_getreg_b32 s100, hwreg(HW_REG_XCC_ID, 0, 4)
	s_and_b32 s100, s100, 15
	s_lshl_b32 s100, s100, 8
	s_add_u32 s100, s100, 0x38e00000
	s_waitcnt lgkmcnt(0)
	s_add_u32 s100, s98, s100
	s_addc_u32 s101, s99, 0
	v_mov_b32_e32 v2, 1
	v_mov_b32_e32 v3, 0x1400
	global_atomic_add v8, v3, v2, s[100:101] sc0
	v_cvt_f32_u32_e32 v12, v4
	v_rcp_iflag_f32_e32 v12, v12
	v_sub_u32_e32 v13, 0, v4
	s_nop 1
	v_mul_f32_e32 v12, 0x4f7ffffe, v12
	v_cvt_u32_f32_e32 v12, v12
	v_mul_lo_u32 v13, v13, v12
	v_mul_hi_u32 v13, v12, v13
	v_add_u32_e32 v12, v12, v13
	s_waitcnt vmcnt(0)
	buffer_inv sc1
	v_mul_hi_u32 v12, v8, v12
	v_mul_lo_u32 v13, v12, v4
	v_sub_u32_e32 v14, v8, v13
	v_add_u32_e32 v15, 1, v12
	v_cmp_ge_u32_e32 vcc, v14, v4
	v_sub_u32_e32 v13, v14, v4
	s_nop 1
	v_cndmask_b32_e32 v12, v12, v15, vcc
	v_cndmask_b32_e32 v14, v14, v13, vcc
	v_add_u32_e32 v15, 1, v12
	v_cmp_ge_u32_e32 vcc, v14, v4
	s_nop 1
	v_cndmask_b32_e32 v6, v12, v15, vcc
	v_add_u32_e32 v9, 1, v6
	v_mul_lo_u32 v10, v9, v4
	v_mul_lo_u32 v11, v9, v5
	v_add_u32_e32 v8, 1, v8
	v_cmp_ne_u32_e32 vcc, v8, v10
	s_cbranch_vccnz .Lxb_spin_10
	v_mov_b32_e32 v3, 0x1480
	v_add_u32_e32 v14, -1, v4
	v_mul_lo_u32 v14, v14, v6
	buffer_wbl2 sc1
	v_mov_b32_e32 v16, 0

.LBB0_1148:
	s_or_b64 exec, exec, s[46:47]
	s_add_i32 s30, s31, 4
	s_cmp_ge_i32 s30, s71
	s_cbranch_scc1 .LBB0_229
	s_cmp_lg_u32 s92, s70
	s_mov_b64 s[42:43], -1
	s_cbranch_scc0 .LBB0_1199
	s_waitcnt vmcnt(0)
	s_barrier
	s_mov_b64 s[42:43], exec
	v_readlane_b32 s2, v253, 6
	v_readlane_b32 s3, v253, 7
	s_and_b64 s[2:3], s[42:43], s[2:3]
	s_mov_b64 exec, s[2:3]
	s_cbranch_execz .LBB0_1198
	v_readlane_b32 s98, v253, 2
	v_readlane_b32 s99, v253, 3
	v_mov_b32_e32 v1, 0x12000
	s_waitcnt vmcnt(0) expcnt(0) lgkmcnt(0)
	s_load_dwordx2 s[98:99], s[98:99], 0xf8
	ds_read_b128 v[4:7], v1
	s_getreg_b32 s100, hwreg(HW_REG_XCC_ID, 0, 4)
	s_and_b32 s100, s100, 15
	s_lshl_b32 s100, s100, 8
	s_add_u32 s100, s100, 0x38e00000
	s_waitcnt lgkmcnt(0)
	s_add_u32 s100, s98, s100
	s_addc_u32 s101, s99, 0
	v_mov_b32_e32 v2, 1
	v_mov_b32_e32 v3, 0x1400
	global_atomic_add v8, v3, v2, s[100:101] sc0
	v_cvt_f32_u32_e32 v12, v4
	v_rcp_iflag_f32_e32 v12, v12
	v_sub_u32_e32 v13, 0, v4
	s_nop 1
	v_mul_f32_e32 v12, 0x4f7ffffe, v12
	v_cvt_u32_f32_e32 v12, v12
	v_mul_lo_u32 v13, v13, v12
	v_mul_hi_u32 v13, v12, v13
	v_add_u32_e32 v12, v12, v13
	s_waitcnt vmcnt(0)
	buffer_inv sc1
	v_mul_hi_u32 v12, v8, v12
	v_mul_lo_u32 v13, v12, v4
	v_sub_u32_e32 v14, v8, v13
	v_add_u32_e32 v15, 1, v12
	v_cmp_ge_u32_e32 vcc, v14, v4
	v_sub_u32_e32 v13, v14, v4
	s_nop 1
	v_cndmask_b32_e32 v12, v12, v15, vcc
	v_cndmask_b32_e32 v14, v14, v13, vcc
	v_add_u32_e32 v15, 1, v12
	v_cmp_ge_u32_e32 vcc, v14, v4
	s_nop 1
	v_cndmask_b32_e32 v6, v12, v15, vcc
	v_add_u32_e32 v9, 1, v6
	v_mul_lo_u32 v10, v9, v4
	v_mul_lo_u32 v11, v9, v5
	v_add_u32_e32 v8, 1, v8
	v_cmp_ne_u32_e32 vcc, v8, v10
	s_cbranch_vccnz .Lxb_spin_11
	v_mov_b32_e32 v3, 0x1480
	v_add_u32_e32 v14, -1, v4
	v_mul_lo_u32 v14, v14, v6
	buffer_wbl2 sc1
	v_mov_b32_e32 v16, 0
